# P7 last round split across WG pairs by row halves + P3 mid-K row-scale loads batched (2 round trips instead of 16)
# speedup vs baseline: 1.0138x; 1.0075x over previous
; __device__ __forceinline__ float sum_f(const float* p, int n4) { float s = 0.f; for (int i = 0; i < n4; ++i) { const f32x4 v = *(const f32x4*)(p + 4 * i); s += (v[0] + v[1]) + (v[2] + v[3]); } return s; }
;     __device__ __forceinline__ void mid(f32x4 (&acc)[2][2][4][2], const Unit& u, int wr, int wc, int fr, int fq) const {
;         asm volatile("" : "+v"(fr), "+v"(fq));
; #pragma unroll
;         for (int ai = 0; ai < 2; ++ai)
; #pragma unroll
;             for (int m = 0; m < 4; ++m) { const size_t row = (size_t)u.pm * BM + ai * HALF + wr * 64 + m * 16 + fr;
;                 const float rf = __builtin_amdgcn_rsqf(sum_f(ssqf + row * 8, 2) * (1.0f / 1024.0f) + RMS_EPS), rl = __builtin_amdgcn_rsqf(sum_f(ssql + row * 8, 2) * (1.0f / 1024.0f) + RMS_EPS);
;                 const float ratio = rf / rl;
; #pragma unroll
;                 for (int bj = 0; bj < 2; ++bj)
; #pragma unroll
;                     for (int n = 0; n < 2; ++n) acc[ai][bj][m][n] = acc[ai][bj][m][n] * ratio;
;                 __builtin_amdgcn_sched_barrier(0); }
.LBB0_1218:
	s_cmpk_lg_i32 s18, 0x800
	s_cbranch_scc1 .LBB0_1217
	v_mov_b32_e32 v2, v152
	v_mov_b32_e32 v1, v153
	s_nop 0
	v_ashrrev_i32_e32 v3, 31, v2
	v_lshl_add_u64 v[2:3], v[2:3], 0, s[26:27]
	v_lshlrev_b64 v[2:3], 3, v[2:3]
	v_lshl_add_u64 v[230:231], v[2:3], 0, s[84:85]
	v_lshlrev_b64 v[230:231], 2, v[230:231]
	v_lshl_add_u64 v[232:233], s[40:41], 0, v[230:231]
	v_lshl_add_u64 v[234:235], s[24:25], 0, v[230:231]
	global_load_dwordx4 v[158:161], v[232:233], off
	global_load_dwordx4 v[162:165], v[232:233], off offset:16
	global_load_dwordx4 v[166:169], v[234:235], off
	global_load_dwordx4 v[170:173], v[234:235], off offset:16
	v_lshl_add_u64 v[230:231], v[2:3], 0, s[86:87]
	v_lshlrev_b64 v[230:231], 2, v[230:231]
	v_lshl_add_u64 v[232:233], s[40:41], 0, v[230:231]
	v_lshl_add_u64 v[234:235], s[24:25], 0, v[230:231]
	global_load_dwordx4 v[174:177], v[232:233], off
	global_load_dwordx4 v[178:181], v[232:233], off offset:16
	global_load_dwordx4 v[182:185], v[234:235], off
	global_load_dwordx4 v[186:189], v[234:235], off offset:16
	v_lshl_add_u64 v[230:231], v[2:3], 0, s[96:97]
	v_lshlrev_b64 v[230:231], 2, v[230:231]
	v_lshl_add_u64 v[232:233], s[40:41], 0, v[230:231]
	v_lshl_add_u64 v[234:235], s[24:25], 0, v[230:231]
	global_load_dwordx4 v[190:193], v[232:233], off
	global_load_dwordx4 v[194:197], v[232:233], off offset:16
	global_load_dwordx4 v[198:201], v[234:235], off
	global_load_dwordx4 v[202:205], v[234:235], off offset:16
	v_lshl_add_u64 v[230:231], v[2:3], 0, s[34:35]
	v_lshlrev_b64 v[230:231], 2, v[230:231]
	v_lshl_add_u64 v[232:233], s[40:41], 0, v[230:231]
	v_lshl_add_u64 v[234:235], s[24:25], 0, v[230:231]
	global_load_dwordx4 v[206:209], v[232:233], off
	global_load_dwordx4 v[210:213], v[232:233], off offset:16
	global_load_dwordx4 v[214:217], v[234:235], off
	global_load_dwordx4 v[218:221], v[234:235], off offset:16
	s_waitcnt vmcnt(12)
	v_add_f32_e32 v238, v158, v159
	v_add_f32_e32 v239, v160, v161
	v_add_f32_e32 v240, v162, v163
	v_add_f32_e32 v241, v164, v165
	v_add_f32_e32 v238, v238, v239
	v_add_f32_e32 v240, v240, v241
	v_add_f32_e32 v242, 0, v238
	v_add_f32_e32 v242, v242, v240
	v_fmamk_f32 v242, v242, 0x3a800000, v155
	v_rsq_f32_e32 v242, v242
	v_add_f32_e32 v238, v166, v167
	v_add_f32_e32 v239, v168, v169
	v_add_f32_e32 v240, v170, v171
	v_add_f32_e32 v241, v172, v173
	v_add_f32_e32 v238, v238, v239
	v_add_f32_e32 v240, v240, v241
	v_add_f32_e32 v243, 0, v238
	v_add_f32_e32 v243, v243, v240
	v_fmamk_f32 v243, v243, 0x3a800000, v155
	v_rsq_f32_e32 v243, v243
	s_nop 0
	v_div_scale_f32 v236, s[42:43], v243, v243, v242
	v_rcp_f32_e32 v237, v236
	s_nop 0
	v_fma_f32 v244, -v236, v237, 1.0
	v_fmac_f32_e32 v237, v244, v237
	v_div_scale_f32 v244, vcc, v242, v243, v242
	v_mul_f32_e32 v245, v244, v237
	v_fma_f32 v246, -v236, v245, v244
	v_fmac_f32_e32 v245, v246, v237
	v_fma_f32 v236, -v236, v245, v244
	v_div_fmas_f32 v236, v236, v237, v245
	v_div_fixup_f32 v236, v236, v243, v242
	v_pk_mul_f32 v[130:131], v[130:131], v[236:237] op_sel_hi:[1,0]
	v_pk_mul_f32 v[128:129], v[128:129], v[236:237] op_sel_hi:[1,0]
	v_pk_mul_f32 v[126:127], v[126:127], v[236:237] op_sel_hi:[1,0]
	v_pk_mul_f32 v[124:125], v[124:125], v[236:237] op_sel_hi:[1,0]
	v_pk_mul_f32 v[122:123], v[122:123], v[236:237] op_sel_hi:[1,0]
	v_pk_mul_f32 v[120:121], v[120:121], v[236:237] op_sel_hi:[1,0]
	v_pk_mul_f32 v[118:119], v[118:119], v[236:237] op_sel_hi:[1,0]
	v_pk_mul_f32 v[116:117], v[116:117], v[236:237] op_sel_hi:[1,0]
	s_waitcnt vmcnt(8)
	v_add_f32_e32 v238, v174, v175
	v_add_f32_e32 v239, v176, v177
	v_add_f32_e32 v240, v178, v179
	v_add_f32_e32 v241, v180, v181
	v_add_f32_e32 v238, v238, v239
	v_add_f32_e32 v240, v240, v241
	v_add_f32_e32 v242, 0, v238
	v_add_f32_e32 v242, v242, v240
	v_fmamk_f32 v242, v242, 0x3a800000, v155
	v_rsq_f32_e32 v242, v242
	v_add_f32_e32 v238, v182, v183
	v_add_f32_e32 v239, v184, v185
	v_add_f32_e32 v240, v186, v187
	v_add_f32_e32 v241, v188, v189
	v_add_f32_e32 v238, v238, v239
	v_add_f32_e32 v240, v240, v241
	v_add_f32_e32 v243, 0, v238
	v_add_f32_e32 v243, v243, v240
	v_fmamk_f32 v243, v243, 0x3a800000, v155
	v_rsq_f32_e32 v243, v243
	s_nop 0
	v_div_scale_f32 v236, s[42:43], v243, v243, v242
	v_rcp_f32_e32 v237, v236
	s_nop 0
	v_fma_f32 v244, -v236, v237, 1.0
	v_fmac_f32_e32 v237, v244, v237
	v_div_scale_f32 v244, vcc, v242, v243, v242
	v_mul_f32_e32 v245, v244, v237
	v_fma_f32 v246, -v236, v245, v244
	v_fmac_f32_e32 v245, v246, v237
	v_fma_f32 v236, -v236, v245, v244
	v_div_fmas_f32 v236, v236, v237, v245
	v_div_fixup_f32 v236, v236, v243, v242
	v_pk_mul_f32 v[114:115], v[114:115], v[236:237] op_sel_hi:[1,0]
	v_pk_mul_f32 v[112:113], v[112:113], v[236:237] op_sel_hi:[1,0]
	v_pk_mul_f32 v[110:111], v[110:111], v[236:237] op_sel_hi:[1,0]
	v_pk_mul_f32 v[108:109], v[108:109], v[236:237] op_sel_hi:[1,0]
	v_pk_mul_f32 v[106:107], v[106:107], v[236:237] op_sel_hi:[1,0]
	v_pk_mul_f32 v[104:105], v[104:105], v[236:237] op_sel_hi:[1,0]
	v_pk_mul_f32 v[102:103], v[102:103], v[236:237] op_sel_hi:[1,0]
	v_pk_mul_f32 v[100:101], v[100:101], v[236:237] op_sel_hi:[1,0]
	s_waitcnt vmcnt(4)
; __device__ __forceinline__ float sum_f(const float* p, int n4) { float s = 0.f; for (int i = 0; i < n4; ++i) { const f32x4 v = *(const f32x4*)(p + 4 * i); s += (v[0] + v[1]) + (v[2] + v[3]); } return s; }
;     __device__ __forceinline__ void mid(f32x4 (&acc)[2][2][4][2], const Unit& u, int wr, int wc, int fr, int fq) const {
;         asm volatile("" : "+v"(fr), "+v"(fq));
; #pragma unroll
;         for (int ai = 0; ai < 2; ++ai)
; #pragma unroll
;             for (int m = 0; m < 4; ++m) { const size_t row = (size_t)u.pm * BM + ai * HALF + wr * 64 + m * 16 + fr;
;                 const float rf = __builtin_amdgcn_rsqf(sum_f(ssqf + row * 8, 2) * (1.0f / 1024.0f) + RMS_EPS), rl = __builtin_amdgcn_rsqf(sum_f(ssql + row * 8, 2) * (1.0f / 1024.0f) + RMS_EPS);
;                 const float ratio = rf / rl;
; #pragma unroll
;                 for (int bj = 0; bj < 2; ++bj)
; #pragma unroll
;                     for (int n = 0; n < 2; ++n) acc[ai][bj][m][n] = acc[ai][bj][m][n] * ratio;
;                 __builtin_amdgcn_sched_barrier(0); }
	v_add_f32_e32 v238, v190, v191
	v_add_f32_e32 v239, v192, v193
	v_add_f32_e32 v240, v194, v195
	v_add_f32_e32 v241, v196, v197
	v_add_f32_e32 v238, v238, v239
	v_add_f32_e32 v240, v240, v241
	v_add_f32_e32 v242, 0, v238
	v_add_f32_e32 v242, v242, v240
	v_fmamk_f32 v242, v242, 0x3a800000, v155
	v_rsq_f32_e32 v242, v242
	v_add_f32_e32 v238, v198, v199
	v_add_f32_e32 v239, v200, v201
	v_add_f32_e32 v240, v202, v203
	v_add_f32_e32 v241, v204, v205
	v_add_f32_e32 v238, v238, v239
	v_add_f32_e32 v240, v240, v241
	v_add_f32_e32 v243, 0, v238
	v_add_f32_e32 v243, v243, v240
	v_fmamk_f32 v243, v243, 0x3a800000, v155
	v_rsq_f32_e32 v243, v243
	s_nop 0
	v_div_scale_f32 v236, s[42:43], v243, v243, v242
	v_rcp_f32_e32 v237, v236
	s_nop 0
	v_fma_f32 v244, -v236, v237, 1.0
	v_fmac_f32_e32 v237, v244, v237
	v_div_scale_f32 v244, vcc, v242, v243, v242
	v_mul_f32_e32 v245, v244, v237
	v_fma_f32 v246, -v236, v245, v244
	v_fmac_f32_e32 v245, v246, v237
	v_fma_f32 v236, -v236, v245, v244
	v_div_fmas_f32 v236, v236, v237, v245
	v_div_fixup_f32 v236, v236, v243, v242
	v_pk_mul_f32 v[98:99], v[98:99], v[236:237] op_sel_hi:[1,0]
	v_pk_mul_f32 v[96:97], v[96:97], v[236:237] op_sel_hi:[1,0]
	v_pk_mul_f32 v[94:95], v[94:95], v[236:237] op_sel_hi:[1,0]
	v_pk_mul_f32 v[92:93], v[92:93], v[236:237] op_sel_hi:[1,0]
	v_pk_mul_f32 v[90:91], v[90:91], v[236:237] op_sel_hi:[1,0]
	v_pk_mul_f32 v[88:89], v[88:89], v[236:237] op_sel_hi:[1,0]
	v_pk_mul_f32 v[86:87], v[86:87], v[236:237] op_sel_hi:[1,0]
	v_pk_mul_f32 v[84:85], v[84:85], v[236:237] op_sel_hi:[1,0]
	s_waitcnt vmcnt(0)
	v_add_f32_e32 v238, v206, v207
	v_add_f32_e32 v239, v208, v209
	v_add_f32_e32 v240, v210, v211
	v_add_f32_e32 v241, v212, v213
	v_add_f32_e32 v238, v238, v239
	v_add_f32_e32 v240, v240, v241
	v_add_f32_e32 v242, 0, v238
	v_add_f32_e32 v242, v242, v240
	v_fmamk_f32 v242, v242, 0x3a800000, v155
	v_rsq_f32_e32 v242, v242
	v_add_f32_e32 v238, v214, v215
	v_add_f32_e32 v239, v216, v217
	v_add_f32_e32 v240, v218, v219
	v_add_f32_e32 v241, v220, v221
	v_add_f32_e32 v238, v238, v239
	v_add_f32_e32 v240, v240, v241
	v_add_f32_e32 v243, 0, v238
	v_add_f32_e32 v243, v243, v240
	v_fmamk_f32 v243, v243, 0x3a800000, v155
	v_rsq_f32_e32 v243, v243
	s_nop 0
	v_div_scale_f32 v236, s[42:43], v243, v243, v242
	v_rcp_f32_e32 v237, v236
	s_nop 0
	v_fma_f32 v244, -v236, v237, 1.0
	v_fmac_f32_e32 v237, v244, v237
	v_div_scale_f32 v244, vcc, v242, v243, v242
	v_mul_f32_e32 v245, v244, v237
	v_fma_f32 v246, -v236, v245, v244
	v_fmac_f32_e32 v245, v246, v237
	v_fma_f32 v236, -v236, v245, v244
	v_div_fmas_f32 v236, v236, v237, v245
	v_div_fixup_f32 v236, v236, v243, v242
	v_pk_mul_f32 v[82:83], v[82:83], v[236:237] op_sel_hi:[1,0]
	v_pk_mul_f32 v[80:81], v[80:81], v[236:237] op_sel_hi:[1,0]
	v_pk_mul_f32 v[78:79], v[78:79], v[236:237] op_sel_hi:[1,0]
	v_pk_mul_f32 v[76:77], v[76:77], v[236:237] op_sel_hi:[1,0]
	v_pk_mul_f32 v[74:75], v[74:75], v[236:237] op_sel_hi:[1,0]
	v_pk_mul_f32 v[72:73], v[72:73], v[236:237] op_sel_hi:[1,0]
	v_pk_mul_f32 v[70:71], v[70:71], v[236:237] op_sel_hi:[1,0]
	v_pk_mul_f32 v[68:69], v[68:69], v[236:237] op_sel_hi:[1,0]
	v_lshl_add_u64 v[230:231], v[2:3], 0, s[82:83]
	v_lshlrev_b64 v[230:231], 2, v[230:231]
	v_lshl_add_u64 v[232:233], s[40:41], 0, v[230:231]
	v_lshl_add_u64 v[234:235], s[24:25], 0, v[230:231]
	global_load_dwordx4 v[158:161], v[232:233], off
	global_load_dwordx4 v[162:165], v[232:233], off offset:16
	global_load_dwordx4 v[166:169], v[234:235], off
	global_load_dwordx4 v[170:173], v[234:235], off offset:16
	v_lshl_add_u64 v[230:231], v[2:3], 0, s[20:21]
	v_lshlrev_b64 v[230:231], 2, v[230:231]
	v_lshl_add_u64 v[232:233], s[40:41], 0, v[230:231]
	v_lshl_add_u64 v[234:235], s[24:25], 0, v[230:231]
	global_load_dwordx4 v[174:177], v[232:233], off
	global_load_dwordx4 v[178:181], v[232:233], off offset:16
	global_load_dwordx4 v[182:185], v[234:235], off
	global_load_dwordx4 v[186:189], v[234:235], off offset:16
	v_lshl_add_u64 v[230:231], v[2:3], 0, s[12:13]
	v_lshlrev_b64 v[230:231], 2, v[230:231]
	v_lshl_add_u64 v[232:233], s[40:41], 0, v[230:231]
	v_lshl_add_u64 v[234:235], s[24:25], 0, v[230:231]
	global_load_dwordx4 v[190:193], v[232:233], off
	global_load_dwordx4 v[194:197], v[232:233], off offset:16
	global_load_dwordx4 v[198:201], v[234:235], off
	global_load_dwordx4 v[202:205], v[234:235], off offset:16
	v_lshl_add_u64 v[230:231], v[2:3], 0, s[16:17]
	v_lshlrev_b64 v[230:231], 2, v[230:231]
	v_lshl_add_u64 v[232:233], s[40:41], 0, v[230:231]
	v_lshl_add_u64 v[234:235], s[24:25], 0, v[230:231]
	global_load_dwordx4 v[206:209], v[232:233], off
	global_load_dwordx4 v[210:213], v[232:233], off offset:16
	global_load_dwordx4 v[214:217], v[234:235], off
	global_load_dwordx4 v[218:221], v[234:235], off offset:16
	s_waitcnt vmcnt(12)
; __device__ __forceinline__ float sum_f(const float* p, int n4) { float s = 0.f; for (int i = 0; i < n4; ++i) { const f32x4 v = *(const f32x4*)(p + 4 * i); s += (v[0] + v[1]) + (v[2] + v[3]); } return s; }
;     __device__ __forceinline__ void mid(f32x4 (&acc)[2][2][4][2], const Unit& u, int wr, int wc, int fr, int fq) const {
;         asm volatile("" : "+v"(fr), "+v"(fq));
; #pragma unroll
;         for (int ai = 0; ai < 2; ++ai)
; #pragma unroll
;             for (int m = 0; m < 4; ++m) { const size_t row = (size_t)u.pm * BM + ai * HALF + wr * 64 + m * 16 + fr;
;                 const float rf = __builtin_amdgcn_rsqf(sum_f(ssqf + row * 8, 2) * (1.0f / 1024.0f) + RMS_EPS), rl = __builtin_amdgcn_rsqf(sum_f(ssql + row * 8, 2) * (1.0f / 1024.0f) + RMS_EPS);
;                 const float ratio = rf / rl;
; #pragma unroll
;                 for (int bj = 0; bj < 2; ++bj)
; #pragma unroll
;                     for (int n = 0; n < 2; ++n) acc[ai][bj][m][n] = acc[ai][bj][m][n] * ratio;
;                 __builtin_amdgcn_sched_barrier(0); }
	v_add_f32_e32 v238, v158, v159
	v_add_f32_e32 v239, v160, v161
	v_add_f32_e32 v240, v162, v163
	v_add_f32_e32 v241, v164, v165
	v_add_f32_e32 v238, v238, v239
	v_add_f32_e32 v240, v240, v241
	v_add_f32_e32 v242, 0, v238
	v_add_f32_e32 v242, v242, v240
	v_fmamk_f32 v242, v242, 0x3a800000, v155
	v_rsq_f32_e32 v242, v242
	v_add_f32_e32 v238, v166, v167
	v_add_f32_e32 v239, v168, v169
	v_add_f32_e32 v240, v170, v171
	v_add_f32_e32 v241, v172, v173
	v_add_f32_e32 v238, v238, v239
	v_add_f32_e32 v240, v240, v241
	v_add_f32_e32 v243, 0, v238
	v_add_f32_e32 v243, v243, v240
	v_fmamk_f32 v243, v243, 0x3a800000, v155
	v_rsq_f32_e32 v243, v243
	s_nop 0
	v_div_scale_f32 v236, s[42:43], v243, v243, v242
	v_rcp_f32_e32 v237, v236
	s_nop 0
	v_fma_f32 v244, -v236, v237, 1.0
	v_fmac_f32_e32 v237, v244, v237
	v_div_scale_f32 v244, vcc, v242, v243, v242
	v_mul_f32_e32 v245, v244, v237
	v_fma_f32 v246, -v236, v245, v244
	v_fmac_f32_e32 v245, v246, v237
	v_fma_f32 v236, -v236, v245, v244
	v_div_fmas_f32 v236, v236, v237, v245
	v_div_fixup_f32 v236, v236, v243, v242
	v_pk_mul_f32 v[66:67], v[66:67], v[236:237] op_sel_hi:[1,0]
	v_pk_mul_f32 v[64:65], v[64:65], v[236:237] op_sel_hi:[1,0]
	v_pk_mul_f32 v[62:63], v[62:63], v[236:237] op_sel_hi:[1,0]
	v_pk_mul_f32 v[60:61], v[60:61], v[236:237] op_sel_hi:[1,0]
	v_pk_mul_f32 v[58:59], v[58:59], v[236:237] op_sel_hi:[1,0]
	v_pk_mul_f32 v[56:57], v[56:57], v[236:237] op_sel_hi:[1,0]
	v_pk_mul_f32 v[54:55], v[54:55], v[236:237] op_sel_hi:[1,0]
	v_pk_mul_f32 v[52:53], v[52:53], v[236:237] op_sel_hi:[1,0]
	s_waitcnt vmcnt(8)
	v_add_f32_e32 v238, v174, v175
	v_add_f32_e32 v239, v176, v177
	v_add_f32_e32 v240, v178, v179
	v_add_f32_e32 v241, v180, v181
	v_add_f32_e32 v238, v238, v239
	v_add_f32_e32 v240, v240, v241
	v_add_f32_e32 v242, 0, v238
	v_add_f32_e32 v242, v242, v240
	v_fmamk_f32 v242, v242, 0x3a800000, v155
	v_rsq_f32_e32 v242, v242
	v_add_f32_e32 v238, v182, v183
	v_add_f32_e32 v239, v184, v185
	v_add_f32_e32 v240, v186, v187
	v_add_f32_e32 v241, v188, v189
	v_add_f32_e32 v238, v238, v239
	v_add_f32_e32 v240, v240, v241
	v_add_f32_e32 v243, 0, v238
	v_add_f32_e32 v243, v243, v240
	v_fmamk_f32 v243, v243, 0x3a800000, v155
	v_rsq_f32_e32 v243, v243
	s_nop 0
	v_div_scale_f32 v236, s[42:43], v243, v243, v242
	v_rcp_f32_e32 v237, v236
	s_nop 0
	v_fma_f32 v244, -v236, v237, 1.0
	v_fmac_f32_e32 v237, v244, v237
	v_div_scale_f32 v244, vcc, v242, v243, v242
	v_mul_f32_e32 v245, v244, v237
	v_fma_f32 v246, -v236, v245, v244
	v_fmac_f32_e32 v245, v246, v237
	v_fma_f32 v236, -v236, v245, v244
	v_div_fmas_f32 v236, v236, v237, v245
	v_div_fixup_f32 v236, v236, v243, v242
	v_pk_mul_f32 v[50:51], v[50:51], v[236:237] op_sel_hi:[1,0]
	v_pk_mul_f32 v[48:49], v[48:49], v[236:237] op_sel_hi:[1,0]
	v_pk_mul_f32 v[46:47], v[46:47], v[236:237] op_sel_hi:[1,0]
	v_pk_mul_f32 v[44:45], v[44:45], v[236:237] op_sel_hi:[1,0]
	v_pk_mul_f32 v[42:43], v[42:43], v[236:237] op_sel_hi:[1,0]
	v_pk_mul_f32 v[40:41], v[40:41], v[236:237] op_sel_hi:[1,0]
	v_pk_mul_f32 v[38:39], v[38:39], v[236:237] op_sel_hi:[1,0]
	v_pk_mul_f32 v[36:37], v[36:37], v[236:237] op_sel_hi:[1,0]
	s_waitcnt vmcnt(4)
	v_add_f32_e32 v238, v190, v191
	v_add_f32_e32 v239, v192, v193
	v_add_f32_e32 v240, v194, v195
	v_add_f32_e32 v241, v196, v197
	v_add_f32_e32 v238, v238, v239
	v_add_f32_e32 v240, v240, v241
	v_add_f32_e32 v242, 0, v238
	v_add_f32_e32 v242, v242, v240
	v_fmamk_f32 v242, v242, 0x3a800000, v155
	v_rsq_f32_e32 v242, v242
	v_add_f32_e32 v238, v198, v199
	v_add_f32_e32 v239, v200, v201
	v_add_f32_e32 v240, v202, v203
	v_add_f32_e32 v241, v204, v205
	v_add_f32_e32 v238, v238, v239
	v_add_f32_e32 v240, v240, v241
	v_add_f32_e32 v243, 0, v238
	v_add_f32_e32 v243, v243, v240
	v_fmamk_f32 v243, v243, 0x3a800000, v155
	v_rsq_f32_e32 v243, v243
	s_nop 0
	v_div_scale_f32 v236, s[42:43], v243, v243, v242
	v_rcp_f32_e32 v237, v236
	s_nop 0
	v_fma_f32 v244, -v236, v237, 1.0
	v_fmac_f32_e32 v237, v244, v237
	v_div_scale_f32 v244, vcc, v242, v243, v242
	v_mul_f32_e32 v245, v244, v237
	v_fma_f32 v246, -v236, v245, v244
	v_fmac_f32_e32 v245, v246, v237
	v_fma_f32 v236, -v236, v245, v244
	v_div_fmas_f32 v236, v236, v237, v245
	v_div_fixup_f32 v236, v236, v243, v242
	v_pk_mul_f32 v[34:35], v[34:35], v[236:237] op_sel_hi:[1,0]
	v_pk_mul_f32 v[32:33], v[32:33], v[236:237] op_sel_hi:[1,0]
	v_pk_mul_f32 v[30:31], v[30:31], v[236:237] op_sel_hi:[1,0]
	v_pk_mul_f32 v[28:29], v[28:29], v[236:237] op_sel_hi:[1,0]
	v_pk_mul_f32 v[26:27], v[26:27], v[236:237] op_sel_hi:[1,0]
	v_pk_mul_f32 v[24:25], v[24:25], v[236:237] op_sel_hi:[1,0]
	v_pk_mul_f32 v[22:23], v[22:23], v[236:237] op_sel_hi:[1,0]
	v_pk_mul_f32 v[20:21], v[20:21], v[236:237] op_sel_hi:[1,0]
	s_waitcnt vmcnt(0)
	v_add_f32_e32 v238, v206, v207
	v_add_f32_e32 v239, v208, v209
	v_add_f32_e32 v240, v210, v211
	v_add_f32_e32 v241, v212, v213
	v_add_f32_e32 v238, v238, v239
	v_add_f32_e32 v240, v240, v241
	v_add_f32_e32 v242, 0, v238
	v_add_f32_e32 v242, v242, v240
	v_fmamk_f32 v242, v242, 0x3a800000, v155
	v_rsq_f32_e32 v242, v242
	v_add_f32_e32 v238, v214, v215
	v_add_f32_e32 v239, v216, v217
	v_add_f32_e32 v240, v218, v219
	v_add_f32_e32 v241, v220, v221
	v_add_f32_e32 v238, v238, v239
	v_add_f32_e32 v240, v240, v241
	v_add_f32_e32 v243, 0, v238
	v_add_f32_e32 v243, v243, v240
	v_fmamk_f32 v243, v243, 0x3a800000, v155
	v_rsq_f32_e32 v243, v243
	s_nop 0
	v_div_scale_f32 v236, s[42:43], v243, v243, v242
	v_rcp_f32_e32 v237, v236
	s_nop 0
	v_fma_f32 v244, -v236, v237, 1.0
	v_fmac_f32_e32 v237, v244, v237
	v_div_scale_f32 v244, vcc, v242, v243, v242
	v_mul_f32_e32 v245, v244, v237
	v_fma_f32 v246, -v236, v245, v244
	v_fmac_f32_e32 v245, v246, v237
	v_fma_f32 v236, -v236, v245, v244
	v_div_fmas_f32 v236, v236, v237, v245
	v_div_fixup_f32 v236, v236, v243, v242
	v_pk_mul_f32 v[18:19], v[18:19], v[236:237] op_sel_hi:[1,0]
	v_pk_mul_f32 v[16:17], v[16:17], v[236:237] op_sel_hi:[1,0]
	v_pk_mul_f32 v[14:15], v[14:15], v[236:237] op_sel_hi:[1,0]
	v_pk_mul_f32 v[12:13], v[12:13], v[236:237] op_sel_hi:[1,0]
	v_pk_mul_f32 v[10:11], v[10:11], v[236:237] op_sel_hi:[1,0]
	v_pk_mul_f32 v[8:9], v[8:9], v[236:237] op_sel_hi:[1,0]
	v_pk_mul_f32 v[6:7], v[6:7], v[236:237] op_sel_hi:[1,0]
	v_pk_mul_f32 v[4:5], v[4:5], v[236:237] op_sel_hi:[1,0]
	s_branch .LBB0_1217
